# speedup vs baseline: 1.0023x; 1.0023x over previous
.Lh2_idle:
	v_readlane_b32 s5, v254, 53
	s_add_i32 s33, s5, s57
	s_cmpk_lt_i32 s33, 0x180
	s_cbranch_scc1 .Lh2_top2
	s_sub_i32 s4, 0x180, s57
	s_lshl_b32 s5, s4, 1
	s_cmp_gt_i32 s5, s42
	s_cbranch_scc1 .LBB0_96
	v_readlane_b32 s5, v254, 53
	s_add_i32 s33, s5, s57
	s_sub_i32 s33, s33, s4
	s_cmpk_lt_i32 s33, 0x180
	s_cbranch_scc0 .LBB0_96
	s_movk_i32 s7, 0x80
	s_branch .Lh2_tile
.Lh2_top:
	v_readlane_b32 s4, v255, 4
	v_readlane_b32 s5, v255, 5
	s_and_b64 vcc, exec, s[4:5]
	s_cbranch_vccnz .Lh2_conv

.Lh2_conv:
	s_mov_b32 s4, -1
	s_cmpk_gt_u32 s33, 0x62b
	v_mbcnt_lo_u32_b32 v0, s4, 0
	v_mbcnt_hi_u32_b32 v0, s4, v0
	v_add_u32_e32 v0, s43, v0
	s_cbranch_scc1 .LBB0_133
	v_ashrrev_i32_e32 v6, 4, v0
	v_and_b32_e32 v2, 15, v0
	v_lshlrev_b32_e32 v3, 2, v6
	v_and_b32_e32 v1, 12, v3
	v_bfe_i32 v4, v6, 2, 1
	s_movk_i32 s4, 0x1600
	v_and_or_b32 v4, v4, s4, v1
	v_lshlrev_b32_e32 v5, 7, v6
	s_movk_i32 s4, 0x200
	v_and_or_b32 v5, v5, s4, v1
	v_lshlrev_b32_e32 v0, 4, v2
	v_lshlrev_b32_e32 v2, 3, v2
	s_sub_i32 s4, 0x180, s57
	s_lshl_b32 s4, s4, 1
	s_cmp_gt_i32 s4, s42
	s_cbranch_scc1 .Lh2_noshare
	v_readlane_b32 s4, v254, 53
	s_add_i32 s59, s4, 0x1b54
	s_mov_b32 s58, s42
.Lh2_noshare:
	s_mov_b32 s36, s59
	s_branch .LBB0_103

.Lh1_idle:
	v_readlane_b32 s7, v254, 53
	s_add_i32 s33, s7, s55
	s_cmpk_lt_i32 s33, 0x180
	s_cbranch_scc1 .Lh1_top2
	s_sub_i32 s6, 0x180, s55
	s_lshl_b32 s7, s6, 1
	s_cmp_gt_i32 s7, s42
	s_cbranch_scc1 .LBB0_213
	v_readlane_b32 s7, v254, 53
	s_add_i32 s33, s7, s55
	s_sub_i32 s33, s33, s6
	s_cmpk_lt_i32 s33, 0x180
	s_cbranch_scc0 .LBB0_213
	s_movk_i32 s59, 0x80
	s_branch .Lh1_tile
.Lh1_top:
	v_readlane_b32 s6, v255, 4
	v_readlane_b32 s7, v255, 5
	s_and_b64 vcc, exec, s[6:7]
	s_cbranch_vccnz .Lh1_conv

.Lh1_conv:
	s_mov_b32 s6, -1
	s_cmpk_gt_u32 s33, 0x49f
	v_mbcnt_lo_u32_b32 v0, s6, 0
	v_mbcnt_hi_u32_b32 v0, s6, v0
	v_add_u32_e32 v0, s43, v0
	s_cbranch_scc1 .LBB0_250
	v_ashrrev_i32_e32 v6, 4, v0
	v_and_b32_e32 v2, 15, v0
	v_lshlrev_b32_e32 v3, 2, v6
	v_and_b32_e32 v1, 12, v3
	v_bfe_i32 v4, v6, 2, 1
	s_movk_i32 s6, 0x1600
	v_and_or_b32 v4, v4, s6, v1
	v_lshlrev_b32_e32 v5, 7, v6
	s_movk_i32 s6, 0x200
	v_and_or_b32 v5, v5, s6, v1
	v_lshlrev_b32_e32 v0, 4, v2
	v_lshlrev_b32_e32 v2, 3, v2
	s_sub_i32 s6, 0x180, s55
	s_lshl_b32 s6, s6, 1
	s_cmp_gt_i32 s6, s42
	s_cbranch_scc1 .Lh1_noshare
	v_readlane_b32 s6, v254, 53
	s_add_i32 s77, s6, 0x1258
	s_mov_b32 s76, s42
.Lh1_noshare:
	s_mov_b32 s36, s77
	s_branch .LBB0_220
